# attention: second K/V staging register set (freed by recomputing per-item address constants), global loads two tiles ahead
# speedup vs baseline: 1.0153x; 1.0153x over previous
; template <int DQK, bool CAUSAL, bool ROPE> ...
;     ...
;     u32x4 sk[2], sk2 = {0u, 0u, 0u, 0u}, sv[2];
;     const unsigned bkA = (unsigned)((tid >> 4) * ldk1 + (tid & 15) * 8) * 2u, bkB = bkA + (unsigned)(32 * ldk1) * 2u;
;     const unsigned bk2 = (unsigned)((tid >> 3) * ldk2 + (tid & 7) * 8) * 2u;
;     const unsigned bvA = (unsigned)((tid >> 3) * ldvt + (tid & 7) * 8) * 2u, bvB = bvA + (unsigned)(64 * ldvt) * 2u;
; __global__ void __launch_bounds__(512, 2) fwd_kernel(Args args) {
;     ...
;         for (int it = vcu; it < NB * NH * 16; it += G) {
;             const int bh = it >> 4, pi = it & 15, b = bh >> 4, h = bh & 15;
;             _Pragma("unroll 1") for (int half = 0; half < 2 * REPA; ++half) {
;                 const int qb = (half & 1) ? pi : 31 - pi;
;                 attn_unit<192, true, true>(lds, wave, WSF(O_CS) + (size_t)b * SEQ * 64, WSB(O_Q) + (size_t)b * SEQ * 3072 + h * DQKH, 3072, WSB(O_KN) + (size_t)b * SEQ * DM + h * 128, DM, WSB(O_KROPE) + (size_t)b * SEQ * 64, 64,
;                                      WSB(O_VT) + (size_t)h * 128 * MTOK + (size_t)b * SEQ, MTOK, WSB(O_ATTO) + (size_t)b * SEQ * DM + h * 128, DM, qb * 256, 4 * qb + 4, C);
.LBB0_880:
	v_readlane_b32 s4, v255, 18
	s_nop 3
	s_and_b32 s4, s4, 0xffffffc0
	v_add_u32_e32 v4, s4, v232
	v_lshlrev_b32_e32 v2, 8, v4
	s_movk_i32 s4, 0xf0f0
	v_ashrrev_i32_e32 v7, 3, v4
	v_bitop3_b32 v168, v2, s4, v233 bitop3:0xc8
	v_lshl_or_b32 v2, v7, 7, v236
	v_lshl_or_b32 v172, v7, 15, v236
	v_add_u32_e32 v174, 0x200000, v172
	v_mov_b32_e32 v173, v3
	v_mov_b32_e32 v175, v3
	s_mov_b64 s[4:5], 0x19000080
	v_lshl_add_u64 v[166:167], v[172:173], 0, s[4:5]
	v_lshl_add_u64 v[180:181], v[174:175], 0, s[4:5]
	s_mov_b64 s[4:5], 0x1f502000
	v_lshl_add_u64 v[182:183], v[2:3], 0, s[4:5]
	v_add_u32_e32 v170, 0x20000, v168
	v_mov_b32_e32 v169, v3
	v_mov_b32_e32 v171, v3
	s_mov_b64 s[4:5], 0x15040000
	v_lshl_add_u64 v[184:185], v[168:169], 0, s[4:5]
	v_lshl_add_u64 v[186:187], v[170:171], 0, s[4:5]
	v_lshrrev_b32_e32 v5, 5, v232
	v_lshlrev_b32_e32 v4, 2, v5
	v_lshlrev_b32_e32 v6, 3, v5
	v_lshlrev_b32_e32 v188, 1, v4
	v_lshlrev_b32_e32 v190, 1, v6
	v_mov_b32_e32 v189, v3
	v_mov_b32_e32 v191, v3
	s_bfe_u32 s2, s70, 0x40004
	s_and_b32 s93, s70, 15
	s_ashr_i32 s0, s70, 8
	s_lshl_b32 s16, s2, 22
	s_lshl_b32 s17, s2, 8
	s_mov_b32 s72, s70
	s_xor_b32 s70, s93, 31
	s_ashr_i32 s1, s0, 31
	s_mul_i32 s4, s0, 0x3000000
	v_readlane_b32 s5, v254, 20
	s_mul_hi_i32 s3, s0, 0x3000000
	s_add_u32 s4, s5, s4
	s_addc_u32 s3, s73, s3
	s_mulk_i32 s2, 0x180
	s_add_u32 s2, s4, s2
	s_addc_u32 s3, s3, 0
	s_lshl_b64 s[4:5], s[0:1], 25
	v_readlane_b32 s6, v255, 17
	s_add_u32 s6, s6, s4
	s_addc_u32 s7, s74, s5
	s_add_u32 s6, s6, s17
	s_addc_u32 s7, s7, 0
	s_add_u32 s10, s75, s16
	s_addc_u32 s11, s76, 0
	s_lshl_b64 s[8:9], s[0:1], 14
	s_add_u32 s10, s10, s8
	s_addc_u32 s11, s11, s9
	s_add_u32 s12, s77, s4
	s_addc_u32 s13, s78, s5
	s_add_u32 s12, s12, s17
	s_addc_u32 s13, s13, 0
	s_lshl_b64 s[14:15], s[0:1], 21
	s_lshl_b64 s[0:1], s[0:1], 20
	v_lshl_add_u64 v[206:207], s[2:3], 0, v[190:191]
	s_add_u32 s2, s8, s16
	s_addc_u32 s3, s9, 0
	s_or_b32 s4, s4, s17
	v_lshl_add_u64 v[192:193], v[0:1], 0, s[14:15]
	v_lshl_add_u64 v[194:195], s[6:7], 0, v[168:169]
	v_lshl_add_u64 v[196:197], s[6:7], 0, v[170:171]
	v_lshl_add_u64 v[198:199], v[230:231], 0, s[0:1]
	v_lshl_add_u64 v[200:201], s[10:11], 0, v[172:173]
	v_lshl_add_u64 v[202:203], s[10:11], 0, v[174:175]
	v_lshl_add_u64 v[204:205], s[12:13], 0, v[188:189]
	v_lshl_add_u64 v[208:209], s[2:3], 0, v[166:167]
	v_lshl_add_u64 v[210:211], s[2:3], 0, v[180:181]
	v_lshl_add_u64 v[212:213], v[182:183], 0, s[0:1]
	v_lshl_add_u64 v[214:215], s[4:5], 0, v[184:185]
	v_lshl_add_u64 v[216:217], s[4:5], 0, v[186:187]
	s_mov_b64 s[0:1], -1
	s_branch .LBB0_882

; #define LAS __attribute__((address_space(3)))
; template <int DQK, bool CAUSAL, bool ROPE> ...
;     ...
;     const int qw0 = q0 + 32 * wid, qrow = qw0 + c;
;     constexpr int NKR = 8;
;     bf16x8 qf[NKR];
; #pragma unroll
;     for (int ks = 0; ks < NKR; ++ks) qf[ks] = *(const bf16x8*)(Qp + (size_t)qrow * ldq + 16 * ks + 8 * hi);
;     LAS unsigned char* qlds = lds + QBASE + wid * ((NKS - NKR) * 1024) + lane * 16;
;     if (ROPE) {
; #pragma unroll
;         for (int ks = NKR; ks < 8; ++ks) *(LAS bf16x8*)(qlds + (ks - NKR) * 1024) = *(const bf16x8*)(Qp + (size_t)qrow * ldq + 16 * ks + 8 * hi);
;         const float* ct = cstab + (size_t)qrow * 64 + 8 * hi;
; #pragma unroll
;         for (int p = 0; p < 2; ++p) {
;             const u32x4 a = *(const u32x4*)(Qp + (size_t)qrow * ldq + 16 * (8 + p) + 8 * hi), b = *(const u32x4*)(Qp + (size_t)qrow * ldq + 16 * (10 + p) + 8 * hi);
;             const f32x4 c0 = *(const f32x4*)(ct + 16 * p), c1 = *(const f32x4*)(ct + 16 * p + 4), s0 = *(const f32x4*)(ct + 32 + 16 * p), s1 = *(const f32x4*)(ct + 32 + 16 * p + 4);
;             const float x1[8] = {bflo(a.x), bfhi(a.x), bflo(a.y), bfhi(a.y), bflo(a.z), bfhi(a.z), bflo(a.w), bfhi(a.w)};
;             const float x2[8] = {bflo(b.x), bfhi(b.x), bflo(b.y), bfhi(b.y), bflo(b.z), bfhi(b.z), bflo(b.w), bfhi(b.w)};
;             const float cc[8] = {c0.x, c0.y, c0.z, c0.w, c1.x, c1.y, c1.z, c1.w}, ss[8] = {s0.x, s0.y, s0.z, s0.w, s1.x, s1.y, s1.z, s1.w};
;             float y1[8], y2[8];
; #pragma unroll
;             for (int e = 0; e < 8; ++e) { y1[e] = x1[e] * cc[e] - x2[e] * ss[e]; y2[e] = x2[e] * cc[e] + x1[e] * ss[e]; }
;             const u32x4 w1 = {pk2(y1[0], y1[1]), pk2(y1[2], y1[3]), pk2(y1[4], y1[5]), pk2(y1[6], y1[7])}, w2 = {pk2(y2[0], y2[1]), pk2(y2[2], y2[3]), pk2(y2[4], y2[5]), pk2(y2[6], y2[7])};
;             *(LAS u32x4*)(qlds + (8 + p - NKR) * 1024) = w1; *(LAS u32x4*)(qlds + (10 + p - NKR) * 1024) = w2;
;         }
;     } else {
; #pragma unroll
;         for (int ks = NKR; ks < NKS; ++ks) *(LAS bf16x8*)(qlds + (ks - NKR) * 1024) = *(const bf16x8*)(Qp + (size_t)qrow * ldq + 16 * ks + 8 * hi);
;     }
;     u32x4 sk[2], sk2 = {0u, 0u, 0u, 0u}, sv[2];
;     const unsigned bkA = (unsigned)((tid >> 4) * ldk1 + (tid & 15) * 8) * 2u, bkB = bkA + (unsigned)(32 * ldk1) * 2u;
;     const unsigned bk2 = (unsigned)((tid >> 3) * ldk2 + (tid & 7) * 8) * 2u;
.LBB0_882:
	s_xor_b64 s[82:83], s[0:1], -1
	s_and_b64 s[0:1], s[0:1], exec
	s_cselect_b32 s1, s70, s93
	s_lshl_b32 s65, s1, 8
	s_add_i32 s3, s65, s79
	v_or_b32_e32 v218, s3, v234
	s_movk_i32 s0, 0x1800
	v_mad_u64_u32 v[52:53], s[4:5], v218, s0, v[206:207]
	v_mov_b32_e32 v219, v3
	global_load_dwordx4 v[4:7], v[52:53], off offset:256
	global_load_dwordx4 v[8:11], v[52:53], off offset:320
	global_load_dwordx4 v[12:15], v[52:53], off offset:288
	v_lshlrev_b64 v[20:21], 8, v[218:219]
	v_lshl_add_u64 v[48:49], v[192:193], 0, v[20:21]
	global_load_dwordx4 v[16:19], v[52:53], off offset:352
	global_load_dwordx4 v[20:23], v[48:49], off offset:128
	global_load_dwordx4 v[24:27], v[48:49], off offset:144
	global_load_dwordx4 v[28:31], v[48:49], off offset:192
	global_load_dwordx4 v[32:35], v[48:49], off
	global_load_dwordx4 v[36:39], v[48:49], off offset:16
	global_load_dwordx4 v[40:43], v[48:49], off offset:64
	global_load_dwordx4 v[44:47], v[48:49], off offset:208
	s_nop 0
	global_load_dwordx4 v[48:51], v[48:49], off offset:80
	s_nop 0
	global_load_dwordx4 v[114:117], v[194:195], off
	global_load_dwordx4 v[122:125], v[196:197], off
	global_load_dwordx4 v[146:149], v[198:199], off
	global_load_dwordx4 v[158:161], v[200:201], off
	global_load_dwordx4 v[118:121], v[52:53], off offset:224
	global_load_dwordx4 v[126:129], v[52:53], off offset:32
	global_load_dwordx4 v[130:133], v[52:53], off offset:64
	global_load_dwordx4 v[134:137], v[52:53], off offset:96
	global_load_dwordx4 v[138:141], v[52:53], off offset:128
	global_load_dwordx4 v[142:145], v[52:53], off offset:160
	global_load_dwordx4 v[150:153], v[52:53], off offset:192
	global_load_dwordx4 v[154:157], v[52:53], off
	global_load_dwordx4 v[162:165], v[202:203], off
	v_add_u32_e32 v249, s91, v233
	v_add_u32_e32 v2, v237, v238
	s_lshl_b32 s33, s1, 2
	s_mov_b32 s0, 2
	s_add_i32 s33, s33, 4
	s_or_b32 s64, s3, 31
	v_add_u32_e32 v251, s65, v246
	s_addk_i32 s65, 0x100
	s_mov_b32 s92, 0
	v_mov_b32_e32 v250, 0
	v_mov_b32_e32 v252, 0xf149f2ca
	v_mov_b32_e32 v90, 0
	v_mov_b32_e32 v91, 0
	v_mov_b32_e32 v92, 0
	v_mov_b32_e32 v93, 0
	v_mov_b32_e32 v82, 0
	v_mov_b32_e32 v83, 0
	v_mov_b32_e32 v84, 0
	v_mov_b32_e32 v85, 0
	v_mov_b32_e32 v94, 0
	v_mov_b32_e32 v95, 0
	v_mov_b32_e32 v96, 0
	v_mov_b32_e32 v97, 0
	v_mov_b32_e32 v86, 0
	v_mov_b32_e32 v87, 0
	v_mov_b32_e32 v88, 0
	v_mov_b32_e32 v89, 0
	v_mov_b64_e32 v[220:221], v[216:217]
	v_mov_b64_e32 v[222:223], v[214:215]
	v_mov_b64_e32 v[224:225], v[212:213]
	v_mov_b64_e32 v[226:227], v[210:211]
	v_mov_b64_e32 v[228:229], v[208:209]
	s_mov_b32 s71, 0
	s_mov_b32 s1, 0
	s_waitcnt vmcnt(24)
	v_lshlrev_b32_e32 v52, 16, v4
	v_and_b32_e32 v53, 0xffff0000, v4
	s_waitcnt vmcnt(23)
	v_lshlrev_b32_e32 v54, 16, v8
	v_and_b32_e32 v55, 0xffff0000, v8
	v_lshlrev_b32_e32 v4, 16, v5
	v_and_b32_e32 v5, 0xffff0000, v5
	v_lshlrev_b32_e32 v8, 16, v9
	v_and_b32_e32 v9, 0xffff0000, v9
	v_lshlrev_b32_e32 v58, 16, v10
	v_and_b32_e32 v59, 0xffff0000, v10
	v_lshlrev_b32_e32 v10, 16, v11
	v_and_b32_e32 v11, 0xffff0000, v11
	v_lshlrev_b32_e32 v56, 16, v6
	v_and_b32_e32 v57, 0xffff0000, v6
	v_lshlrev_b32_e32 v6, 16, v7
	v_and_b32_e32 v7, 0xffff0000, v7
	s_waitcnt vmcnt(20)
	v_pk_mul_f32 v[64:65], v[20:21], v[54:55]
	v_pk_mul_f32 v[20:21], v[20:21], v[52:53]
	v_pk_mul_f32 v[66:67], v[22:23], v[8:9]
	v_pk_mul_f32 v[22:23], v[22:23], v[4:5]
	s_waitcnt vmcnt(19)
	v_pk_mul_f32 v[68:69], v[24:25], v[58:59]
	v_pk_mul_f32 v[70:71], v[26:27], v[10:11]
	v_pk_mul_f32 v[24:25], v[24:25], v[56:57]
	v_pk_mul_f32 v[26:27], v[26:27], v[6:7]
	s_waitcnt vmcnt(17)
	v_pk_fma_f32 v[52:53], v[32:33], v[52:53], v[64:65] neg_lo:[0,0,1] neg_hi:[0,0,1]
	v_pk_fma_f32 v[20:21], v[32:33], v[54:55], v[20:21]
	v_pk_fma_f32 v[32:33], v[34:35], v[4:5], v[66:67] neg_lo:[0,0,1] neg_hi:[0,0,1]
	v_pk_fma_f32 v[22:23], v[34:35], v[8:9], v[22:23]
	s_waitcnt vmcnt(16)
	v_pk_fma_f32 v[8:9], v[36:37], v[56:57], v[68:69] neg_lo:[0,0,1] neg_hi:[0,0,1]
	v_pk_fma_f32 v[34:35], v[38:39], v[6:7], v[70:71] neg_lo:[0,0,1] neg_hi:[0,0,1]
	v_lshlrev_b32_e32 v60, 16, v12
	v_and_b32_e32 v61, 0xffff0000, v12
	v_lshlrev_b32_e32 v12, 16, v13
	v_and_b32_e32 v13, 0xffff0000, v13
	v_pk_fma_f32 v[24:25], v[36:37], v[58:59], v[24:25]
	v_pk_fma_f32 v[26:27], v[38:39], v[10:11], v[26:27]
	v_cvt_pk_bf16_f32 v4, v52, v53
	v_cvt_pk_bf16_f32 v5, v32, v33
	v_cvt_pk_bf16_f32 v6, v8, v9
	v_cvt_pk_bf16_f32 v7, v34, v35
	v_cvt_pk_bf16_f32 v8, v20, v21
	v_cvt_pk_bf16_f32 v9, v22, v23
	v_cvt_pk_bf16_f32 v10, v24, v25
	v_cvt_pk_bf16_f32 v11, v26, v27
	ds_write_b128 v249, v[4:7]
	ds_write_b128 v249, v[8:11] offset:2048
	v_lshlrev_b32_e32 v4, 16, v17
	v_and_b32_e32 v5, 0xffff0000, v17
	v_pk_mul_f32 v[8:9], v[30:31], v[12:13]
	v_pk_mul_f32 v[6:7], v[30:31], v[4:5]
	s_waitcnt vmcnt(15)
; template <int DQK, bool CAUSAL, bool ROPE> ...
;     ...
;     if (ROPE) {
; #pragma unroll
;         for (int ks = NKR; ks < 8; ++ks) *(LAS bf16x8*)(qlds + (ks - NKR) * 1024) = *(const bf16x8*)(Qp + (size_t)qrow * ldq + 16 * ks + 8 * hi);
;         const float* ct = cstab + (size_t)qrow * 64 + 8 * hi;
; #pragma unroll
;         for (int p = 0; p < 2; ++p) {
;             const u32x4 a = *(const u32x4*)(Qp + (size_t)qrow * ldq + 16 * (8 + p) + 8 * hi), b = *(const u32x4*)(Qp + (size_t)qrow * ldq + 16 * (10 + p) + 8 * hi);
;             const f32x4 c0 = *(const f32x4*)(ct + 16 * p), c1 = *(const f32x4*)(ct + 16 * p + 4), s0 = *(const f32x4*)(ct + 32 + 16 * p), s1 = *(const f32x4*)(ct + 32 + 16 * p + 4);
;             const float x1[8] = {bflo(a.x), bfhi(a.x), bflo(a.y), bfhi(a.y), bflo(a.z), bfhi(a.z), bflo(a.w), bfhi(a.w)};
;             const float x2[8] = {bflo(b.x), bfhi(b.x), bflo(b.y), bfhi(b.y), bflo(b.z), bfhi(b.z), bflo(b.w), bfhi(b.w)};
;             const float cc[8] = {c0.x, c0.y, c0.z, c0.w, c1.x, c1.y, c1.z, c1.w}, ss[8] = {s0.x, s0.y, s0.z, s0.w, s1.x, s1.y, s1.z, s1.w};
;             float y1[8], y2[8];
; #pragma unroll
;             for (int e = 0; e < 8; ++e) { y1[e] = x1[e] * cc[e] - x2[e] * ss[e]; y2[e] = x2[e] * cc[e] + x1[e] * ss[e]; }
;             const u32x4 w1 = {pk2(y1[0], y1[1]), pk2(y1[2], y1[3]), pk2(y1[4], y1[5]), pk2(y1[6], y1[7])}, w2 = {pk2(y2[0], y2[1]), pk2(y2[2], y2[3]), pk2(y2[4], y2[5]), pk2(y2[6], y2[7])};
;             *(LAS u32x4*)(qlds + (8 + p - NKR) * 1024) = w1; *(LAS u32x4*)(qlds + (10 + p - NKR) * 1024) = w2;
;         }
;     } else {
; #pragma unroll
;         for (int ks = NKR; ks < NKS; ++ks) *(LAS bf16x8*)(qlds + (ks - NKR) * 1024) = *(const bf16x8*)(Qp + (size_t)qrow * ldq + 16 * ks + 8 * hi);
;     }
;     u32x4 sk[2], sk2 = {0u, 0u, 0u, 0u}, sv[2];
;     const unsigned bkA = (unsigned)((tid >> 4) * ldk1 + (tid & 15) * 8) * 2u, bkB = bkA + (unsigned)(32 * ldk1) * 2u;
;     const unsigned bk2 = (unsigned)((tid >> 3) * ldk2 + (tid & 7) * 8) * 2u;
;     const unsigned bvA = (unsigned)((tid >> 3) * ldvt + (tid & 7) * 8) * 2u, bvB = bvA + (unsigned)(64 * ldvt) * 2u;
;     ...
;     AT_LOAD(0); AT_STORE(0, 0);
;     __syncthreads();
;     const int pm_ = (c & 3) | ((c & 4) << 1) | ((c & 8) >> 1) | (c & 16);
;     const int koff = pm_ * KROW + hi * 16, voff = VBASE + c * VROW + hi * 16;
;     const int grp = wid >> 2;
	v_pk_fma_f32 v[10:11], v[42:43], v[4:5], v[8:9]
	v_lshlrev_b32_e32 v8, 16, v18
	v_and_b32_e32 v9, 0xffff0000, v18
	v_pk_fma_f32 v[6:7], v[42:43], v[12:13], v[6:7] neg_lo:[0,0,1] neg_hi:[0,0,1]
	v_lshlrev_b32_e32 v4, 16, v14
	v_and_b32_e32 v5, 0xffff0000, v14
	s_waitcnt vmcnt(14)
	v_pk_mul_f32 v[12:13], v[44:45], v[8:9]
	v_lshlrev_b32_e32 v62, 16, v16
	s_waitcnt vmcnt(13)
	v_pk_fma_f32 v[12:13], v[48:49], v[4:5], v[12:13] neg_lo:[0,0,1] neg_hi:[0,0,1]
	v_pk_mul_f32 v[4:5], v[44:45], v[4:5]
	v_and_b32_e32 v63, 0xffff0000, v16
	v_pk_fma_f32 v[16:17], v[48:49], v[8:9], v[4:5]
	v_lshlrev_b32_e32 v8, 16, v19
	v_and_b32_e32 v9, 0xffff0000, v19
	v_pk_mul_f32 v[72:73], v[28:29], v[60:61]
	v_pk_mul_f32 v[28:29], v[28:29], v[62:63]
	v_lshlrev_b32_e32 v4, 16, v15
	v_and_b32_e32 v5, 0xffff0000, v15
	v_pk_mul_f32 v[14:15], v[46:47], v[8:9]
	v_pk_fma_f32 v[28:29], v[40:41], v[60:61], v[28:29] neg_lo:[0,0,1] neg_hi:[0,0,1]
	v_pk_fma_f32 v[14:15], v[50:51], v[4:5], v[14:15] neg_lo:[0,0,1] neg_hi:[0,0,1]
	v_pk_mul_f32 v[4:5], v[46:47], v[4:5]
	v_pk_fma_f32 v[36:37], v[40:41], v[62:63], v[72:73]
	v_pk_fma_f32 v[18:19], v[50:51], v[8:9], v[4:5]
	v_cvt_pk_bf16_f32 v4, v28, v29
	v_cvt_pk_bf16_f32 v5, v6, v7
	v_cvt_pk_bf16_f32 v6, v12, v13
	v_cvt_pk_bf16_f32 v7, v14, v15
	v_cvt_pk_bf16_f32 v8, v36, v37
	v_cvt_pk_bf16_f32 v9, v10, v11
	v_cvt_pk_bf16_f32 v10, v16, v17
	v_cvt_pk_bf16_f32 v11, v18, v19
	ds_write_b128 v249, v[4:7] offset:1024
	ds_write_b128 v249, v[8:11] offset:3072
	s_waitcnt vmcnt(12)
	ds_write_b128 v2, v[114:117]
	v_add_u32_e32 v2, v237, v239
	s_waitcnt vmcnt(11)
	ds_write_b128 v2, v[122:125]
	s_waitcnt vmcnt(10)
	ds_write_b128 v247, v[146:149] offset:256
	v_add_u32_e32 v2, v241, v242
	s_waitcnt vmcnt(9)
	ds_write_b128 v2, v[158:161] offset:51200
	v_add_u32_e32 v2, v241, v243
	v_mov_b32_e32 v16, v3
	v_mov_b32_e32 v17, v3
	s_waitcnt vmcnt(0)
	ds_write_b128 v2, v[162:165] offset:51200
	v_mov_b32_e32 v2, v3
	v_mov_b32_e32 v4, v3
	v_mov_b32_e32 v5, v3
	v_mov_b32_e32 v6, v3
	v_mov_b32_e32 v7, v3
	v_mov_b32_e32 v8, v3
	v_mov_b32_e32 v9, v3
	v_mov_b32_e32 v10, v3
	v_mov_b32_e32 v11, v3
	v_mov_b32_e32 v12, v3
	v_mov_b32_e32 v13, v3
	v_mov_b32_e32 v14, v3
	v_mov_b32_e32 v15, v3
	v_mov_b64_e32 v[32:33], v[16:17]
	v_mov_b64_e32 v[48:49], v[16:17]
	v_mov_b64_e32 v[64:65], v[16:17]
	v_mov_b64_e32 v[80:81], v[16:17]
	v_mov_b64_e32 v[30:31], v[14:15]
	v_mov_b64_e32 v[28:29], v[12:13]
	v_mov_b64_e32 v[26:27], v[10:11]
	v_mov_b64_e32 v[24:25], v[8:9]
	v_mov_b64_e32 v[22:23], v[6:7]
	v_mov_b64_e32 v[20:21], v[4:5]
	v_mov_b64_e32 v[18:19], v[2:3]
	v_mov_b64_e32 v[46:47], v[14:15]
	v_mov_b64_e32 v[44:45], v[12:13]
	v_mov_b64_e32 v[42:43], v[10:11]
	v_mov_b64_e32 v[40:41], v[8:9]
	v_mov_b64_e32 v[38:39], v[6:7]
	v_mov_b64_e32 v[36:37], v[4:5]
	v_mov_b64_e32 v[34:35], v[2:3]
	v_mov_b64_e32 v[62:63], v[14:15]
	v_mov_b64_e32 v[60:61], v[12:13]
	v_mov_b64_e32 v[58:59], v[10:11]
	v_mov_b64_e32 v[56:57], v[8:9]
	v_mov_b64_e32 v[54:55], v[6:7]
	v_mov_b64_e32 v[52:53], v[4:5]
	v_mov_b64_e32 v[50:51], v[2:3]
	v_mov_b64_e32 v[78:79], v[14:15]
	v_mov_b64_e32 v[76:77], v[12:13]
	v_mov_b64_e32 v[74:75], v[10:11]
	v_mov_b64_e32 v[72:73], v[8:9]
	v_mov_b64_e32 v[70:71], v[6:7]
	v_mov_b64_e32 v[68:69], v[4:5]
	v_mov_b64_e32 v[66:67], v[2:3]
	global_load_dwordx4 v[114:117], v222, s[96:97]
	global_load_dwordx4 v[122:125], v220, s[96:97]
	global_load_dwordx4 v[146:149], v224, s[96:97]
	global_load_dwordx4 v[158:161], v228, s[96:97]
	global_load_dwordx4 v[162:165], v226, s[96:97]
	s_mov_b64 s[4:5], 0x2000
	v_lshl_add_u64 v[228:229], v[228:229], 0, s[94:95]
	v_lshl_add_u64 v[226:227], v[226:227], 0, s[94:95]
	v_lshl_add_u64 v[224:225], v[224:225], 0, s[4:5]
	v_lshl_add_u64 v[222:223], v[222:223], 0, s[80:81]
	v_lshl_add_u64 v[220:221], v[220:221], 0, s[80:81]
	s_waitcnt lgkmcnt(0)
	s_barrier
.LBB0_883:
	s_add_i32 s2, s1, 1
	s_cmp_lt_u32 s2, s33
	s_cselect_b64 s[66:67], -1, 0
	s_add_i32 s4, s1, 2
	s_cmp_ge_u32 s4, s33
	s_cbranch_scc1 .LBB0_885
	s_bitcmp1_b32 s1, 0
	s_cbranch_scc1 .Lld_setx
	global_load_dwordx4 v[166:169], v222, s[96:97]
	global_load_dwordx4 v[170:173], v220, s[96:97]
	global_load_dwordx4 v[180:183], v224, s[96:97]
	global_load_dwordx4 v[184:187], v228, s[96:97]
	global_load_dwordx4 v[188:191], v226, s[96:97]
	s_branch .LBB0_885
.Lld_setx:
	global_load_dwordx4 v[114:117], v222, s[96:97]
	global_load_dwordx4 v[122:125], v220, s[96:97]
	global_load_dwordx4 v[146:149], v224, s[96:97]
	global_load_dwordx4 v[158:161], v228, s[96:97]
	global_load_dwordx4 v[162:165], v226, s[96:97]

; template <int DQK, bool CAUSAL, bool ROPE> ...
;     ...
;         if (more) AT_STORE((j + 1) & 1, vnext);
.LBB0_889:
	s_add_i32 s0, s71, 1
	s_cmp_lg_u32 s71, 2
	s_cselect_b32 s1, s0, 0
	s_andn2_b64 vcc, exec, s[66:67]
	s_cbranch_vccnz .LBB0_891
	s_bitcmp1_b32 s2, 0
	s_cselect_b32 s0, 0x6400, 0
	v_add_u32_e32 v2, s0, v235
	v_add_u32_e32 v4, v2, v238
	v_add_u32_e32 v5, v2, v239
	v_add3_u32 v6, s0, v240, v236
	s_mul_i32 s4, s1, 0x4800
	v_add_u32_e32 v2, s4, v241
	v_add_u32_e32 v7, v2, v242
	v_add_u32_e32 v2, v2, v243
	s_add_i32 s5, s2, 1
	s_cmp_lt_u32 s5, s33
	s_cbranch_scc1 .Lw_wait5
	s_waitcnt vmcnt(0)
	s_branch .Lw_go
.Lw_wait5:
	s_waitcnt vmcnt(5)
.Lw_go:
	s_bitcmp1_b32 s2, 0
	s_cbranch_scc0 .Lw_sety
	ds_write_b128 v4, v[114:117]
	ds_write_b128 v5, v[122:125]
	ds_write_b128 v6, v[146:149] offset:256
	ds_write_b128 v7, v[158:161] offset:51200
	ds_write_b128 v2, v[162:165] offset:51200
	s_branch .LBB0_891
.Lw_sety:
	ds_write_b128 v4, v[166:169]
	ds_write_b128 v5, v[170:173]
	ds_write_b128 v6, v[180:183] offset:256
	ds_write_b128 v7, v[184:187] offset:51200
	ds_write_b128 v2, v[188:191] offset:51200
